# fin2 + spatial W-hoist + spatial epilogue loads (b_spatial, u rows) prefetched together instead of 4 serialized rounds
# speedup vs baseline: 1.0292x; 1.0292x over previous
.LBB0_182:
	v_lshl_add_u64 v[12:13], s[26:27], 0, v[78:79]
	s_waitcnt lgkmcnt(0)
	s_barrier
	global_load_dwordx4 v[200:203], v[12:13], off offset:16
	global_load_dwordx4 v[204:207], v[12:13], off
	global_load_dwordx4 v[208:211], v[12:13], off offset:-16
	global_load_dwordx4 v[212:215], v[12:13], off offset:-32
	s_mov_b64 s[0:1], 0xa1d0800
	v_lshl_add_u64 v[16:17], v[36:37], 0, s[6:7]
	v_lshl_add_u64 v[0:1], s[26:27], 0, v[60:61]
	v_lshl_add_u64 v[10:11], v[0:1], 0, s[0:1]
	s_mov_b32 s0, 0xa1d0000
	v_add_co_u32_e64 v0, s[40:41], s0, v0
	v_lshl_add_u64 v[4:5], v[34:35], 0, s[6:7]
	s_nop 0
	v_addc_co_u32_e64 v1, s[40:41], 0, v1, s[40:41]
	ds_read_b32 v19, v85
	ds_read_b32 v18, v86
	global_load_dwordx4 v[6:9], v[0:1], off offset:2048
	s_nop 0
	global_load_dwordx4 v[0:3], v[10:11], off offset:48
	global_load_dwordx4 v[12:15], v[10:11], off offset:32
	global_load_dwordx4 v[20:23], v[10:11], off offset:16
	global_load_dwordx4 v[24:27], v[4:5], off offset:48
	global_load_dwordx4 v[28:31], v[4:5], off offset:32
	global_load_dwordx4 v[80:83], v[4:5], off offset:16
	global_load_dwordx4 v[118:121], v[4:5], off
	global_load_dwordx4 v[122:125], v[16:17], off offset:48
	global_load_dwordx4 v[126:129], v[16:17], off offset:32
	global_load_dwordx4 v[130:133], v[16:17], off offset:16
	global_load_dwordx4 v[134:137], v[16:17], off
	v_lshl_add_u64 v[60:61], v[60:61], 0, s[66:67]
	s_waitcnt vmcnt(12)
	ds_write_b128 v84, v[212:215]
	ds_write_b128 v84, v[208:211] offset:16
	ds_write_b128 v84, v[204:207] offset:32
	ds_write_b128 v84, v[200:203] offset:48
	s_waitcnt vmcnt(11)
	v_lshlrev_b32_e32 v10, 16, v6
	v_and_b32_e32 v6, 0xffff0000, v6
	s_waitcnt lgkmcnt(5)
	v_sub_f32_e32 v10, v10, v19
	v_sub_f32_e32 v6, v6, v19
	s_waitcnt lgkmcnt(4)
	v_mul_f32_e32 v10, v18, v10
	v_mul_f32_e32 v6, v18, v6
	s_waitcnt vmcnt(0)
	v_fma_f32 v10, v118, v10, v134
	v_fma_f32 v6, v119, v6, v135
	v_cvt_pk_bf16_f32 v10, v10, s0
	v_cvt_pk_bf16_f32 v6, v6, s0
	ds_write_b16 v87, v10 offset:34816
	ds_write_b16 v88, v6 offset:34816
	v_lshlrev_b32_e32 v6, 16, v7
	v_sub_f32_e32 v6, v6, v19
	v_and_b32_e32 v7, 0xffff0000, v7
	v_mul_f32_e32 v6, v18, v6
	v_sub_f32_e32 v7, v7, v19
	v_fma_f32 v6, v6, v120, v136
	v_mul_f32_e32 v7, v18, v7
	v_fmac_f32_e32 v137, v7, v121
	v_cvt_pk_bf16_f32 v6, v6, s0
	ds_write_b16 v89, v6 offset:34816
	v_cvt_pk_bf16_f32 v6, v137, s0
	ds_write_b16 v90, v6 offset:34816
	v_lshlrev_b32_e32 v6, 16, v8
	v_sub_f32_e32 v6, v6, v19
	v_and_b32_e32 v7, 0xffff0000, v8
	v_mul_f32_e32 v6, v18, v6
	v_sub_f32_e32 v7, v7, v19
	v_fma_f32 v6, v6, v80, v130
	v_mul_f32_e32 v7, v18, v7
	v_fma_f32 v7, v7, v81, v131
	v_cvt_pk_bf16_f32 v6, v6, s0
	ds_write_b16 v91, v6 offset:34816
	v_cvt_pk_bf16_f32 v6, v7, s0
	ds_write_b16 v92, v6 offset:34816
	v_lshlrev_b32_e32 v6, 16, v9
	v_sub_f32_e32 v6, v6, v19
	v_and_b32_e32 v7, 0xffff0000, v9
	v_mul_f32_e32 v6, v18, v6
	v_sub_f32_e32 v7, v7, v19
	v_fma_f32 v6, v6, v82, v132
	v_mul_f32_e32 v7, v18, v7
	v_fmac_f32_e32 v133, v7, v83
	v_cvt_pk_bf16_f32 v6, v6, s0
	ds_write_b16 v93, v6 offset:34816
	v_cvt_pk_bf16_f32 v6, v133, s0
	ds_write_b16 v94, v6 offset:34816
	v_lshlrev_b32_e32 v6, 16, v20
	v_sub_f32_e32 v6, v6, v19
	v_and_b32_e32 v7, 0xffff0000, v20
	v_mul_f32_e32 v6, v18, v6
	v_sub_f32_e32 v7, v7, v19
	v_fma_f32 v6, v28, v6, v126
	v_mul_f32_e32 v7, v18, v7
	v_fma_f32 v7, v29, v7, v127
	v_cvt_pk_bf16_f32 v6, v6, s0
	ds_write_b16 v87, v6 offset:35088
	v_cvt_pk_bf16_f32 v6, v7, s0
	ds_write_b16 v95, v6 offset:34816
	v_lshlrev_b32_e32 v6, 16, v21
	v_sub_f32_e32 v6, v6, v19
	v_and_b32_e32 v7, 0xffff0000, v21
	v_mul_f32_e32 v6, v18, v6
	v_sub_f32_e32 v7, v7, v19
	v_fma_f32 v6, v6, v30, v128
	v_mul_f32_e32 v7, v18, v7
	v_fmac_f32_e32 v129, v7, v31
	v_cvt_pk_bf16_f32 v6, v6, s0
	ds_write_b16 v96, v6 offset:34816
	v_cvt_pk_bf16_f32 v6, v129, s0
	ds_write_b16 v97, v6 offset:34816
	v_lshlrev_b32_e32 v6, 16, v22
	v_sub_f32_e32 v6, v6, v19
	v_and_b32_e32 v7, 0xffff0000, v22
	v_mul_f32_e32 v6, v18, v6
	v_sub_f32_e32 v7, v7, v19
	v_fma_f32 v6, v6, v24, v122
	v_mul_f32_e32 v7, v18, v7
	v_fma_f32 v7, v7, v25, v123
	v_cvt_pk_bf16_f32 v6, v6, s0
	ds_write_b16 v98, v6 offset:34816
	v_cvt_pk_bf16_f32 v6, v7, s0
	ds_write_b16 v99, v6 offset:34816
	v_lshlrev_b32_e32 v6, 16, v23
	v_sub_f32_e32 v6, v6, v19
	v_and_b32_e32 v7, 0xffff0000, v23
	v_mul_f32_e32 v6, v18, v6
	v_sub_f32_e32 v7, v7, v19
	v_fma_f32 v6, v6, v26, v124
	v_mul_f32_e32 v7, v18, v7
	v_fmac_f32_e32 v125, v7, v27
	v_cvt_pk_bf16_f32 v6, v6, s0
	ds_write_b16 v100, v6 offset:34816
	v_cvt_pk_bf16_f32 v6, v125, s0
	ds_write_b16 v101, v6 offset:34816
	v_lshlrev_b32_e32 v6, 16, v12
	v_sub_f32_e32 v6, v6, v19
	v_mul_f32_e32 v41, v18, v6
	global_load_dwordx4 v[8:11], v[4:5], off offset:112
	global_load_dwordx4 v[20:23], v[4:5], off offset:96
	global_load_dwordx4 v[24:27], v[4:5], off offset:80
	global_load_dwordx4 v[28:31], v[4:5], off offset:64
	s_nop 0
	global_load_dwordx4 v[4:7], v[16:17], off offset:112
	global_load_dwordx4 v[80:83], v[16:17], off offset:96
	global_load_dwordx4 v[118:121], v[16:17], off offset:80
	global_load_dwordx4 v[122:125], v[16:17], off offset:64
	v_and_b32_e32 v12, 0xffff0000, v12
	v_sub_f32_e32 v12, v12, v19
	v_mul_f32_e32 v12, v18, v12
	s_waitcnt vmcnt(0)
	v_fma_f32 v16, v28, v41, v122
	v_fma_f32 v12, v29, v12, v123
	v_cvt_pk_bf16_f32 v16, v16, s0
	v_cvt_pk_bf16_f32 v12, v12, s0
	ds_write_b16 v87, v16 offset:35360
	ds_write_b16 v102, v12 offset:34816
	v_lshlrev_b32_e32 v12, 16, v13
	v_sub_f32_e32 v12, v12, v19
	v_and_b32_e32 v13, 0xffff0000, v13
	v_mul_f32_e32 v12, v18, v12
	v_sub_f32_e32 v13, v13, v19
	v_fma_f32 v12, v12, v30, v124
	v_mul_f32_e32 v13, v18, v13
	v_fmac_f32_e32 v125, v13, v31
	v_cvt_pk_bf16_f32 v12, v12, s0
	ds_write_b16 v103, v12 offset:34816
	v_cvt_pk_bf16_f32 v12, v125, s0
	ds_write_b16 v104, v12 offset:34816
	v_lshlrev_b32_e32 v12, 16, v14
	v_sub_f32_e32 v12, v12, v19
	v_and_b32_e32 v13, 0xffff0000, v14
	v_mul_f32_e32 v12, v18, v12
	v_sub_f32_e32 v13, v13, v19
	v_fma_f32 v12, v12, v24, v118
	v_mul_f32_e32 v13, v18, v13
	v_fma_f32 v13, v13, v25, v119
	v_cvt_pk_bf16_f32 v12, v12, s0
	ds_write_b16 v105, v12 offset:34816
	v_cvt_pk_bf16_f32 v12, v13, s0
	ds_write_b16 v106, v12 offset:34816
	v_lshlrev_b32_e32 v12, 16, v15
	v_sub_f32_e32 v12, v12, v19
	v_and_b32_e32 v13, 0xffff0000, v15
	v_mul_f32_e32 v12, v18, v12
	v_sub_f32_e32 v13, v13, v19
	v_fma_f32 v12, v12, v26, v120
	v_mul_f32_e32 v13, v18, v13
	v_fmac_f32_e32 v121, v13, v27
	v_cvt_pk_bf16_f32 v12, v12, s0
	ds_write_b16 v107, v12 offset:34816
	v_cvt_pk_bf16_f32 v12, v121, s0
	ds_write_b16 v108, v12 offset:34816
	v_lshlrev_b32_e32 v12, 16, v0
	v_and_b32_e32 v0, 0xffff0000, v0
	v_sub_f32_e32 v12, v12, v19
	v_sub_f32_e32 v0, v0, v19
	v_mul_f32_e32 v12, v18, v12
	v_mul_f32_e32 v0, v18, v0
	v_fma_f32 v12, v20, v12, v80
	v_fma_f32 v0, v21, v0, v81
	v_cvt_pk_bf16_f32 v12, v12, s0
	v_cvt_pk_bf16_f32 v0, v0, s0
	ds_write_b16 v109, v12 offset:34816
	ds_write_b16 v110, v0 offset:34816
	v_lshlrev_b32_e32 v0, 16, v1
	v_sub_f32_e32 v0, v0, v19
	v_and_b32_e32 v1, 0xffff0000, v1
	v_mul_f32_e32 v0, v18, v0
	v_sub_f32_e32 v1, v1, v19
	v_fma_f32 v0, v0, v22, v82
	v_mul_f32_e32 v1, v18, v1
	v_fmac_f32_e32 v83, v1, v23
	v_cvt_pk_bf16_f32 v0, v0, s0
	ds_write_b16 v111, v0 offset:34816
	v_cvt_pk_bf16_f32 v0, v83, s0
	ds_write_b16 v112, v0 offset:34816
	v_lshlrev_b32_e32 v0, 16, v2
	v_sub_f32_e32 v0, v0, v19
	v_and_b32_e32 v1, 0xffff0000, v2
	v_mul_f32_e32 v0, v18, v0
	v_sub_f32_e32 v1, v1, v19
	v_fma_f32 v0, v0, v8, v4
	v_mul_f32_e32 v1, v18, v1
	v_fma_f32 v1, v1, v9, v5
	v_cvt_pk_bf16_f32 v0, v0, s0
	ds_write_b16 v113, v0 offset:34816
	v_cvt_pk_bf16_f32 v0, v1, s0
	ds_write_b16 v114, v0 offset:34816
	v_lshlrev_b32_e32 v0, 16, v3
	v_sub_f32_e32 v0, v0, v19
	v_and_b32_e32 v1, 0xffff0000, v3
	v_mul_f32_e32 v0, v18, v0
	v_sub_f32_e32 v1, v1, v19
	v_fma_f32 v0, v0, v10, v6
	v_mul_f32_e32 v1, v18, v1
	v_fmac_f32_e32 v7, v1, v11
	v_cvt_pk_bf16_f32 v0, v0, s0
	ds_write_b16 v115, v0 offset:34816
	v_cvt_pk_bf16_f32 v0, v7, s0
	ds_write_b16 v116, v0 offset:34816
	s_waitcnt lgkmcnt(0)
	s_barrier
	ds_read_b128 v[0:3], v32
	ds_read_b128 v[4:7], v117 offset:34816
	ds_read_b128 v[8:11], v117 offset:39168
	ds_read_b128 v[12:15], v117 offset:43520
	ds_read_b128 v[16:19], v117 offset:47872
	ds_read_b128 v[20:23], v117 offset:52224
	ds_read_b128 v[24:27], v117 offset:56576
	ds_read_b128 v[28:31], v117 offset:60928
	ds_read_b128 v[80:83], v117 offset:65280
	s_waitcnt lgkmcnt(7)
	v_mfma_f32_16x16x32_bf16 v[4:7], v[0:3], v[4:7], 0
	s_mov_b64 s[0:1], 0x8000
	v_lshl_add_u64 v[78:79], v[78:79], 0, s[0:1]
	s_waitcnt lgkmcnt(6)
	v_mfma_f32_16x16x32_bf16 v[8:11], v[0:3], v[8:11], 0
	s_waitcnt lgkmcnt(5)
	v_mfma_f32_16x16x32_bf16 v[12:15], v[0:3], v[12:15], 0
	s_waitcnt lgkmcnt(4)
	v_mfma_f32_16x16x32_bf16 v[16:19], v[0:3], v[16:19], 0
	s_waitcnt lgkmcnt(3)
	v_mfma_f32_16x16x32_bf16 v[20:23], v[0:3], v[20:23], 0
	s_waitcnt lgkmcnt(2)
	v_mfma_f32_16x16x32_bf16 v[24:27], v[0:3], v[24:27], 0
	s_waitcnt lgkmcnt(1)
	v_mfma_f32_16x16x32_bf16 v[28:31], v[0:3], v[28:31], 0
	s_waitcnt lgkmcnt(0)
	v_mfma_f32_16x16x32_bf16 v[0:3], v[0:3], v[80:83], 0
	ds_read_b128 v[80:83], v32 offset:64
	ds_read_b128 v[118:121], v117 offset:34880
	s_waitcnt lgkmcnt(0)
	v_mfma_f32_16x16x32_bf16 v[4:7], v[80:83], v[118:121], v[4:7]
	ds_read_b128 v[118:121], v117 offset:39232
	s_waitcnt lgkmcnt(0)
	v_mfma_f32_16x16x32_bf16 v[8:11], v[80:83], v[118:121], v[8:11]
	ds_read_b128 v[118:121], v117 offset:43584
	s_waitcnt lgkmcnt(0)
	v_mfma_f32_16x16x32_bf16 v[12:15], v[80:83], v[118:121], v[12:15]
	ds_read_b128 v[118:121], v117 offset:47936
	s_waitcnt lgkmcnt(0)
	v_mfma_f32_16x16x32_bf16 v[16:19], v[80:83], v[118:121], v[16:19]
	ds_read_b128 v[118:121], v117 offset:52288
	s_waitcnt lgkmcnt(0)
	v_mfma_f32_16x16x32_bf16 v[20:23], v[80:83], v[118:121], v[20:23]
	ds_read_b128 v[118:121], v117 offset:56640
	s_waitcnt lgkmcnt(0)
	v_mfma_f32_16x16x32_bf16 v[24:27], v[80:83], v[118:121], v[24:27]
	ds_read_b128 v[118:121], v117 offset:60992
	s_waitcnt lgkmcnt(0)
	v_mfma_f32_16x16x32_bf16 v[28:31], v[80:83], v[118:121], v[28:31]
	ds_read_b128 v[118:121], v117 offset:65344
	s_waitcnt lgkmcnt(0)
	v_mfma_f32_16x16x32_bf16 v[0:3], v[80:83], v[118:121], v[0:3]
	ds_read_b128 v[80:83], v32 offset:128
	ds_read_b128 v[118:121], v117 offset:34944
	s_waitcnt lgkmcnt(0)
	v_mfma_f32_16x16x32_bf16 v[4:7], v[80:83], v[118:121], v[4:7]
	ds_read_b128 v[118:121], v117 offset:39296
	s_waitcnt lgkmcnt(0)
	v_mfma_f32_16x16x32_bf16 v[8:11], v[80:83], v[118:121], v[8:11]
	ds_read_b128 v[118:121], v117 offset:43648
	s_waitcnt lgkmcnt(0)
	v_mfma_f32_16x16x32_bf16 v[12:15], v[80:83], v[118:121], v[12:15]
	ds_read_b128 v[118:121], v117 offset:48000
	s_waitcnt lgkmcnt(0)
	v_mfma_f32_16x16x32_bf16 v[16:19], v[80:83], v[118:121], v[16:19]
	ds_read_b128 v[118:121], v117 offset:52352
	s_waitcnt lgkmcnt(0)
	v_mfma_f32_16x16x32_bf16 v[20:23], v[80:83], v[118:121], v[20:23]
	ds_read_b128 v[118:121], v117 offset:56704
	s_waitcnt lgkmcnt(0)
	v_mfma_f32_16x16x32_bf16 v[24:27], v[80:83], v[118:121], v[24:27]
	ds_read_b128 v[118:121], v117 offset:61056
	s_waitcnt lgkmcnt(0)
	v_mfma_f32_16x16x32_bf16 v[28:31], v[80:83], v[118:121], v[28:31]
	ds_read_b128 v[118:121], v117 offset:65408
	s_waitcnt lgkmcnt(0)
	v_mfma_f32_16x16x32_bf16 v[80:83], v[80:83], v[118:121], v[0:3]
	ds_read_b128 v[118:121], v32 offset:192
	s_nop 1
	ds_read_b128 v[0:3], v117 offset:35008
	s_waitcnt lgkmcnt(0)
	v_mfma_f32_16x16x32_bf16 v[0:3], v[118:121], v[0:3], v[4:7]
	s_nop 2
	ds_read_b128 v[4:7], v117 offset:39360
	s_waitcnt lgkmcnt(0)
	v_mfma_f32_16x16x32_bf16 v[4:7], v[118:121], v[4:7], v[8:11]
	s_nop 2
	ds_read_b128 v[8:11], v117 offset:43712
	s_waitcnt lgkmcnt(0)
	v_mfma_f32_16x16x32_bf16 v[8:11], v[118:121], v[8:11], v[12:15]
	s_nop 2
	ds_read_b128 v[12:15], v117 offset:48064
	s_waitcnt lgkmcnt(0)
	v_mfma_f32_16x16x32_bf16 v[12:15], v[118:121], v[12:15], v[16:19]
	s_nop 2
	ds_read_b128 v[16:19], v117 offset:52416
	s_waitcnt lgkmcnt(0)
	v_mfma_f32_16x16x32_bf16 v[16:19], v[118:121], v[16:19], v[20:23]
	s_nop 2
	ds_read_b128 v[20:23], v117 offset:56768
	s_waitcnt lgkmcnt(0)
	v_mfma_f32_16x16x32_bf16 v[20:23], v[118:121], v[20:23], v[24:27]
	s_nop 2
	ds_read_b128 v[24:27], v117 offset:61120
	s_waitcnt lgkmcnt(0)
	v_mfma_f32_16x16x32_bf16 v[24:27], v[118:121], v[24:27], v[28:31]
	s_nop 2
	ds_read_b128 v[28:31], v117 offset:65472
	s_waitcnt lgkmcnt(0)
	v_mfma_f32_16x16x32_bf16 v[28:31], v[118:121], v[28:31], v[80:83]
	s_nop 2
	v_lshl_add_u64 v[80:81], v[44:45], 0, s[6:7]
	v_lshl_add_u64 v[82:83], s[26:27], 0, v[66:67]
	global_load_dwordx4 v[216:219], v[80:81], off
	global_load_dwordx4 v[220:223], v[82:83], off
	v_lshl_add_u64 v[236:237], s[26:27], 0, v[68:69]
	global_load_dwordx4 v[224:227], v[236:237], off
	v_lshl_add_u64 v[236:237], s[26:27], 0, v[70:71]
	global_load_dwordx4 v[228:231], v[236:237], off
	v_lshl_add_u64 v[236:237], s[26:27], 0, v[72:73]
	global_load_dwordx4 v[232:235], v[236:237], off
	v_lshl_add_u64 v[82:83], s[26:27], 0, v[74:75]
	s_add_u32 s6, s6, 0x200
	s_addc_u32 s7, s7, 0
	v_lshl_add_u64 v[66:67], v[66:67], 0, s[66:67]
	v_lshl_add_u64 v[74:75], v[74:75], 0, s[66:67]
	s_cmpk_eq_i32 s6, 0x1000
	s_waitcnt vmcnt(0)
	v_add_f32_e32 v0, v0, v216
	v_lshlrev_b32_e32 v49, 16, v220
	v_mul_f32_e32 v0, v0, v49
	v_and_b32_e32 v49, 0xffff0000, v220
	v_add_f32_e32 v4, v4, v216
	v_mul_f32_e32 v4, v4, v49
	v_cvt_pk_bf16_f32 v118, v0, v4
	v_lshlrev_b32_e32 v0, 16, v221
	v_add_f32_e32 v4, v8, v216
	v_mul_f32_e32 v0, v4, v0
	v_and_b32_e32 v4, 0xffff0000, v221
	v_add_f32_e32 v8, v12, v216
	v_mul_f32_e32 v4, v8, v4
	v_cvt_pk_bf16_f32 v119, v0, v4
	v_lshlrev_b32_e32 v0, 16, v222
	v_add_f32_e32 v4, v16, v216
	v_mul_f32_e32 v0, v4, v0
	v_and_b32_e32 v4, 0xffff0000, v222
	v_add_f32_e32 v8, v20, v216
	v_mul_f32_e32 v4, v8, v4
	v_cvt_pk_bf16_f32 v120, v0, v4
	v_lshlrev_b32_e32 v0, 16, v223
	v_add_f32_e32 v4, v24, v216
	v_mul_f32_e32 v0, v4, v0
	v_and_b32_e32 v4, 0xffff0000, v223
	v_add_f32_e32 v8, v28, v216
	v_mul_f32_e32 v4, v8, v4
	v_cvt_pk_bf16_f32 v121, v0, v4
	global_store_dwordx4 v[82:83], v[118:121], off
	v_lshl_add_u64 v[68:69], v[68:69], 0, s[66:67]
	v_add_f32_e32 v1, v1, v217
	v_lshlrev_b32_e32 v4, 16, v224
	v_mul_f32_e32 v1, v1, v4
	v_and_b32_e32 v4, 0xffff0000, v224
	v_add_f32_e32 v5, v5, v217
	v_mul_f32_e32 v4, v5, v4
	v_cvt_pk_bf16_f32 v118, v1, v4
	v_lshlrev_b32_e32 v1, 16, v225
	v_add_f32_e32 v4, v9, v217
	v_mul_f32_e32 v1, v4, v1
	v_and_b32_e32 v4, 0xffff0000, v225
	v_add_f32_e32 v5, v13, v217
	v_mul_f32_e32 v4, v5, v4
	v_cvt_pk_bf16_f32 v119, v1, v4
	v_lshlrev_b32_e32 v1, 16, v226
	v_add_f32_e32 v4, v17, v217
	v_mul_f32_e32 v1, v4, v1
	v_and_b32_e32 v4, 0xffff0000, v226
	v_add_f32_e32 v5, v21, v217
	v_mul_f32_e32 v4, v5, v4
	v_cvt_pk_bf16_f32 v120, v1, v4
	v_lshlrev_b32_e32 v1, 16, v227
	v_add_f32_e32 v4, v25, v217
	v_mul_f32_e32 v1, v4, v1
	v_and_b32_e32 v4, 0xffff0000, v227
	v_add_f32_e32 v0, v29, v217
	v_mul_f32_e32 v0, v0, v4
	v_cvt_pk_bf16_f32 v121, v1, v0
	v_lshl_add_u64 v[0:1], s[26:27], 0, v[76:77]
	global_store_dwordx4 v[0:1], v[118:121], off
	v_lshl_add_u64 v[70:71], v[70:71], 0, s[66:67]
	v_lshl_add_u64 v[76:77], v[76:77], 0, s[66:67]
	v_add_f32_e32 v1, v2, v218
	v_lshlrev_b32_e32 v0, 16, v228
	v_mul_f32_e32 v0, v1, v0
	v_and_b32_e32 v1, 0xffff0000, v228
	v_add_f32_e32 v2, v6, v218
	v_mul_f32_e32 v1, v2, v1
	v_cvt_pk_bf16_f32 v118, v0, v1
	v_lshlrev_b32_e32 v0, 16, v229
	v_add_f32_e32 v1, v10, v218
	v_mul_f32_e32 v0, v1, v0
	v_and_b32_e32 v1, 0xffff0000, v229
	v_add_f32_e32 v2, v14, v218
	v_mul_f32_e32 v1, v2, v1
	v_cvt_pk_bf16_f32 v119, v0, v1
	v_lshlrev_b32_e32 v0, 16, v230
	v_add_f32_e32 v1, v18, v218
	v_mul_f32_e32 v0, v1, v0
	v_and_b32_e32 v1, 0xffff0000, v230
	v_add_f32_e32 v2, v22, v218
	v_mul_f32_e32 v1, v2, v1
	v_cvt_pk_bf16_f32 v120, v0, v1
	v_lshlrev_b32_e32 v0, 16, v231
	v_add_f32_e32 v1, v26, v218
	v_mul_f32_e32 v0, v1, v0
	v_and_b32_e32 v1, 0xffff0000, v231
	v_add_f32_e32 v2, v30, v218
	v_mul_f32_e32 v1, v2, v1
	v_cvt_pk_bf16_f32 v121, v0, v1
	v_lshl_add_u64 v[0:1], s[26:27], 0, v[64:65]
	global_store_dwordx4 v[0:1], v[118:121], off
	v_lshl_add_u64 v[64:65], v[64:65], 0, s[66:67]
	v_lshl_add_u64 v[72:73], v[72:73], 0, s[66:67]
	v_add_f32_e32 v1, v3, v219
	v_add_f32_e32 v2, v7, v219
	v_lshlrev_b32_e32 v0, 16, v232
	v_mul_f32_e32 v0, v1, v0
	v_and_b32_e32 v1, 0xffff0000, v232
	v_mul_f32_e32 v1, v2, v1
	v_cvt_pk_bf16_f32 v0, v0, v1
	v_lshlrev_b32_e32 v1, 16, v233
	v_add_f32_e32 v2, v11, v219
	v_mul_f32_e32 v1, v2, v1
	v_and_b32_e32 v2, 0xffff0000, v233
	v_add_f32_e32 v3, v15, v219
	v_mul_f32_e32 v2, v3, v2
	v_cvt_pk_bf16_f32 v1, v1, v2
	v_lshlrev_b32_e32 v2, 16, v234
	v_add_f32_e32 v3, v19, v219
	v_mul_f32_e32 v2, v3, v2
	v_and_b32_e32 v3, 0xffff0000, v234
	v_add_f32_e32 v5, v23, v219
	v_mul_f32_e32 v3, v5, v3
	v_cvt_pk_bf16_f32 v2, v2, v3
	v_lshlrev_b32_e32 v3, 16, v235
	v_add_f32_e32 v5, v27, v219
	v_mul_f32_e32 v3, v5, v3
	v_and_b32_e32 v5, 0xffff0000, v235
	v_add_f32_e32 v4, v31, v219
	v_mul_f32_e32 v4, v4, v5
	v_cvt_pk_bf16_f32 v3, v3, v4
	v_lshl_add_u64 v[4:5], s[26:27], 0, v[62:63]
	v_lshl_add_u64 v[62:63], v[62:63], 0, s[66:67]
	global_store_dwordx4 v[4:5], v[0:3], off
	s_cbranch_scc0 .LBB0_182
	s_add_i32 s8, s8, s62
	v_add_u32_e32 v40, s3, v40
	v_add_u32_e32 v48, s3, v48
	v_add_u32_e32 v50, s3, v50
	v_add_u32_e32 v52, s3, v52
	v_add_u32_e32 v56, s3, v56
	s_cmp_ge_i32 s8, s5
	v_add_u32_e32 v58, s3, v58
	s_barrier
	s_cbranch_scc0 .LBB0_177
	v_readlane_b32 s76, v250, 16
	v_readlane_b32 s68, v250, 23
	v_readlane_b32 s70, v250, 25
	v_readlane_b32 s80, v250, 27
	v_readlane_b32 s78, v250, 15
	v_readlane_b32 s77, v250, 17
	v_readlane_b32 s74, v250, 18
	v_readlane_b32 s73, v250, 21
	v_readlane_b32 s65, v250, 22
	v_readlane_b32 s69, v250, 24
	v_readlane_b32 s71, v250, 26
	v_readlane_b32 s81, v250, 28
	s_mov_b32 s75, 0x11000
	s_movk_i32 s79, 0x60
	s_movk_i32 s64, 0x1000
	s_mov_b32 s72, 0x3f07dc22

.Lfin2_check:
	v_add_u32_e32 v72, s74, v0
	v_cmp_gt_i32_e32 vcc, s0, v72
	s_nop 4
	s_cbranch_vccz .LBB0_189
	v_ashrrev_i32_e32 v1, 31, v0
	v_lshlrev_b64 v[24:25], 12, v[0:1]
	v_lshl_add_u64 v[36:37], v[2:3], 0, v[24:25]
	global_load_dwordx4 v[24:27], v[36:37], off offset:16
	global_load_dwordx4 v[28:31], v[36:37], off
	global_load_dwordx4 v[32:35], v[36:37], off offset:272
	global_load_dwordx4 v[36:39], v[36:37], off offset:256
	v_ashrrev_i32_e32 v73, 31, v72
	v_lshlrev_b64 v[50:51], 12, v[72:73]
	v_lshl_add_u64 v[62:63], v[2:3], 0, v[50:51]
	global_load_dwordx4 v[50:53], v[62:63], off offset:16
	global_load_dwordx4 v[54:57], v[62:63], off
	global_load_dwordx4 v[58:61], v[62:63], off offset:272
	global_load_dwordx4 v[62:65], v[62:63], off offset:256
	s_waitcnt vmcnt(6)
	v_lshlrev_b32_e32 v40, 16, v28
	v_and_b32_e32 v28, 0xffff0000, v28
	s_waitcnt vmcnt(4)
	v_lshlrev_b32_e32 v41, 16, v36
	v_and_b32_e32 v36, 0xffff0000, v36
	v_fma_f32 v40, -v6, v41, v40
	v_fma_f32 v36, -v6, v36, v28
	v_lshlrev_b32_e32 v28, 16, v29
	v_lshlrev_b32_e32 v41, 16, v37
	v_fma_f32 v41, -v6, v41, v28
	v_and_b32_e32 v28, 0xffff0000, v29
	v_and_b32_e32 v29, 0xffff0000, v37
	v_mul_f32_e32 v44, v36, v36
	v_fma_f32 v37, -v6, v29, v28
	v_lshlrev_b32_e32 v28, 16, v30
	v_lshlrev_b32_e32 v29, 16, v38
	v_fmac_f32_e32 v44, v40, v40
	v_fma_f32 v42, -v6, v29, v28
	v_and_b32_e32 v28, 0xffff0000, v30
	v_and_b32_e32 v29, 0xffff0000, v38
	v_fmac_f32_e32 v44, v41, v41
	v_fma_f32 v38, -v6, v29, v28
	v_lshlrev_b32_e32 v28, 16, v31
	v_lshlrev_b32_e32 v29, 16, v39
	v_fmac_f32_e32 v44, v37, v37
	v_fma_f32 v43, -v6, v29, v28
	v_and_b32_e32 v28, 0xffff0000, v31
	v_and_b32_e32 v29, 0xffff0000, v39
	v_fmac_f32_e32 v44, v42, v42
	v_fma_f32 v39, -v6, v29, v28
	v_fmac_f32_e32 v44, v38, v38
	v_and_b32_e32 v28, 0xffff0000, v24
	v_lshlrev_b32_e32 v29, 16, v24
	v_and_b32_e32 v30, 0xffff0000, v32
	v_lshlrev_b32_e32 v31, 16, v32
	v_fmac_f32_e32 v44, v43, v43
	v_pk_fma_f32 v[28:29], v[6:7], v[30:31], v[28:29] neg_lo:[1,0,0] neg_hi:[1,0,0]
	v_fmac_f32_e32 v44, v39, v39
	v_pk_mul_f32 v[30:31], v[28:29], v[28:29]
	s_nop 0
	v_add_f32_e32 v24, v31, v44
	v_add_f32_e32 v32, v30, v24
	v_and_b32_e32 v24, 0xffff0000, v25
	v_lshlrev_b32_e32 v25, 16, v25
	v_and_b32_e32 v30, 0xffff0000, v33
	v_lshlrev_b32_e32 v31, 16, v33
	v_pk_fma_f32 v[30:31], v[6:7], v[30:31], v[24:25] neg_lo:[1,0,0] neg_hi:[1,0,0]
	v_lshlrev_b32_e32 v33, 16, v34
	v_pk_mul_f32 v[24:25], v[30:31], v[30:31]
	s_nop 0
	v_add_f32_e32 v25, v25, v32
	v_add_f32_e32 v44, v24, v25
	v_and_b32_e32 v24, 0xffff0000, v26
	v_lshlrev_b32_e32 v25, 16, v26
	v_and_b32_e32 v32, 0xffff0000, v34
	v_pk_fma_f32 v[32:33], v[6:7], v[32:33], v[24:25] neg_lo:[1,0,0] neg_hi:[1,0,0]
	v_and_b32_e32 v26, 0xffff0000, v35
	v_pk_mul_f32 v[24:25], v[32:33], v[32:33]
	s_nop 0
	v_add_f32_e32 v25, v25, v44
	v_add_f32_e32 v44, v24, v25
	v_and_b32_e32 v24, 0xffff0000, v27
	v_lshlrev_b32_e32 v25, 16, v27
	v_lshlrev_b32_e32 v27, 16, v35
	v_pk_fma_f32 v[34:35], v[6:7], v[26:27], v[24:25] neg_lo:[1,0,0] neg_hi:[1,0,0]
	s_nop 0
	v_pk_mul_f32 v[24:25], v[34:35], v[34:35]
	s_nop 0
	v_add_f32_e32 v25, v25, v44
	v_add_f32_e32 v24, v24, v25
	ds_swizzle_b32 v25, v24 offset:swizzle(SWAP,1)
	s_waitcnt lgkmcnt(0)
	v_add_f32_e32 v24, v24, v25
	ds_swizzle_b32 v25, v24 offset:swizzle(SWAP,2)
	s_waitcnt lgkmcnt(0)
	v_add_f32_e32 v24, v24, v25
	ds_swizzle_b32 v25, v24 offset:swizzle(SWAP,4)
	s_waitcnt lgkmcnt(0)
	v_add_f32_e32 v24, v24, v25
	v_fmamk_f32 v24, v24, 0x3c000000, v169
	v_cmp_gt_f32_e32 vcc, s85, v24
	v_mul_f32_e32 v25, 0x4b800000, v24
	s_nop 0
	v_cndmask_b32_e32 v24, v24, v25, vcc
	v_rsq_f32_e32 v24, v24
	s_nop 0
	v_mul_f32_e32 v25, 0x45800000, v24
	v_cndmask_b32_e32 v44, v24, v25, vcc
	v_mul_f32_e32 v24, v40, v44
	v_mul_f32_e32 v25, v36, v44
	v_mul_f32_e32 v24, v8, v24
	v_mul_f32_e32 v25, v9, v25
	v_cvt_pk_bf16_f32 v24, v24, v25
	v_mul_f32_e32 v25, v29, v44
	v_mul_f32_e32 v26, v28, v44
	v_mul_f32_e32 v25, v16, v25
	v_mul_f32_e32 v26, v17, v26
	v_cvt_pk_bf16_f32 v28, v25, v26
	v_mul_f32_e32 v25, v41, v44
	v_mul_f32_e32 v26, v37, v44
	v_mul_f32_e32 v25, v10, v25
	v_mul_f32_e32 v26, v11, v26
	v_cvt_pk_bf16_f32 v25, v25, v26
	v_mul_f32_e32 v26, v31, v44
	v_mul_f32_e32 v27, v30, v44
	v_mul_f32_e32 v26, v18, v26
	v_mul_f32_e32 v27, v19, v27
	v_cvt_pk_bf16_f32 v29, v26, v27
	v_mul_f32_e32 v26, v42, v44
	v_mul_f32_e32 v27, v38, v44
	v_mul_f32_e32 v26, v12, v26
	v_mul_f32_e32 v27, v13, v27
	v_cvt_pk_bf16_f32 v26, v26, v27
	v_mul_f32_e32 v27, v33, v44
	v_mul_f32_e32 v30, v32, v44
	v_mul_f32_e32 v27, v20, v27
	v_mul_f32_e32 v30, v21, v30
	v_cvt_pk_bf16_f32 v30, v27, v30
	v_mul_f32_e32 v27, v43, v44
	v_mul_f32_e32 v31, v39, v44
	v_mul_f32_e32 v27, v14, v27
	v_mul_f32_e32 v31, v15, v31
	v_cvt_pk_bf16_f32 v27, v27, v31
	v_mul_f32_e32 v31, v35, v44
	v_mul_f32_e32 v32, v34, v44
	v_mul_f32_e32 v31, v22, v31
	v_mul_f32_e32 v32, v23, v32
	v_cvt_pk_bf16_f32 v31, v31, v32
	v_lshlrev_b64 v[32:33], 11, v[0:1]
	v_lshl_add_u64 v[32:33], v[4:5], 0, v[32:33]
	s_waitcnt vmcnt(2)
	v_lshlrev_b32_e32 v66, 16, v54
	v_and_b32_e32 v54, 0xffff0000, v54
	s_waitcnt vmcnt(0)
	v_lshlrev_b32_e32 v67, 16, v62
	v_and_b32_e32 v62, 0xffff0000, v62
	v_fma_f32 v66, -v6, v67, v66
	v_fma_f32 v62, -v6, v62, v54
	v_lshlrev_b32_e32 v54, 16, v55
	v_lshlrev_b32_e32 v67, 16, v63
	v_fma_f32 v67, -v6, v67, v54
	v_and_b32_e32 v54, 0xffff0000, v55
	v_and_b32_e32 v55, 0xffff0000, v63
	v_mul_f32_e32 v70, v62, v62
	v_fma_f32 v63, -v6, v55, v54
	v_lshlrev_b32_e32 v54, 16, v56
	v_lshlrev_b32_e32 v55, 16, v64
	v_fmac_f32_e32 v70, v66, v66
	v_fma_f32 v68, -v6, v55, v54
	v_and_b32_e32 v54, 0xffff0000, v56
	v_and_b32_e32 v55, 0xffff0000, v64
	v_fmac_f32_e32 v70, v67, v67
	v_fma_f32 v64, -v6, v55, v54
	v_lshlrev_b32_e32 v54, 16, v57
	v_lshlrev_b32_e32 v55, 16, v65
	v_fmac_f32_e32 v70, v63, v63
	v_fma_f32 v69, -v6, v55, v54
	v_and_b32_e32 v54, 0xffff0000, v57
	v_and_b32_e32 v55, 0xffff0000, v65
	v_fmac_f32_e32 v70, v68, v68
	v_fma_f32 v65, -v6, v55, v54
	v_fmac_f32_e32 v70, v64, v64
	v_and_b32_e32 v54, 0xffff0000, v50
	v_lshlrev_b32_e32 v55, 16, v50
	v_and_b32_e32 v56, 0xffff0000, v58
	v_lshlrev_b32_e32 v57, 16, v58
	v_fmac_f32_e32 v70, v69, v69
	v_pk_fma_f32 v[54:55], v[6:7], v[56:57], v[54:55] neg_lo:[1,0,0] neg_hi:[1,0,0]
	v_fmac_f32_e32 v70, v65, v65
	v_pk_mul_f32 v[56:57], v[54:55], v[54:55]
	s_nop 0
	v_add_f32_e32 v50, v57, v70
	v_add_f32_e32 v58, v56, v50
	v_and_b32_e32 v50, 0xffff0000, v51
	v_lshlrev_b32_e32 v51, 16, v51
	v_and_b32_e32 v56, 0xffff0000, v59
	v_lshlrev_b32_e32 v57, 16, v59
	v_pk_fma_f32 v[56:57], v[6:7], v[56:57], v[50:51] neg_lo:[1,0,0] neg_hi:[1,0,0]
	v_lshlrev_b32_e32 v59, 16, v60
	v_pk_mul_f32 v[50:51], v[56:57], v[56:57]
	s_nop 0
	v_add_f32_e32 v51, v51, v58
	v_add_f32_e32 v70, v50, v51
	v_and_b32_e32 v50, 0xffff0000, v52
	v_lshlrev_b32_e32 v51, 16, v52
	v_and_b32_e32 v58, 0xffff0000, v60
	v_pk_fma_f32 v[58:59], v[6:7], v[58:59], v[50:51] neg_lo:[1,0,0] neg_hi:[1,0,0]
	v_and_b32_e32 v52, 0xffff0000, v61
	v_pk_mul_f32 v[50:51], v[58:59], v[58:59]
	s_nop 0
	v_add_f32_e32 v51, v51, v70
	v_add_f32_e32 v70, v50, v51
	v_and_b32_e32 v50, 0xffff0000, v53
	v_lshlrev_b32_e32 v51, 16, v53
	v_lshlrev_b32_e32 v53, 16, v61
	v_pk_fma_f32 v[60:61], v[6:7], v[52:53], v[50:51] neg_lo:[1,0,0] neg_hi:[1,0,0]
	s_nop 0
	v_pk_mul_f32 v[50:51], v[60:61], v[60:61]
	s_nop 0
	v_add_f32_e32 v51, v51, v70
	v_add_f32_e32 v50, v50, v51
	ds_swizzle_b32 v51, v50 offset:swizzle(SWAP,1)
	s_waitcnt lgkmcnt(0)
	v_add_f32_e32 v50, v50, v51
	ds_swizzle_b32 v51, v50 offset:swizzle(SWAP,2)
	s_waitcnt lgkmcnt(0)
	v_add_f32_e32 v50, v50, v51
	ds_swizzle_b32 v51, v50 offset:swizzle(SWAP,4)
	s_waitcnt lgkmcnt(0)
	v_add_f32_e32 v50, v50, v51
	v_fmamk_f32 v50, v50, 0x3c000000, v169
	v_cmp_gt_f32_e32 vcc, s85, v50
	v_mul_f32_e32 v51, 0x4b800000, v50
	s_nop 0
	v_cndmask_b32_e32 v50, v50, v51, vcc
	v_rsq_f32_e32 v50, v50
	s_nop 0
	v_mul_f32_e32 v51, 0x45800000, v50
	v_cndmask_b32_e32 v70, v50, v51, vcc
	v_mul_f32_e32 v50, v66, v70
	v_mul_f32_e32 v51, v62, v70
	v_mul_f32_e32 v50, v8, v50
	v_mul_f32_e32 v51, v9, v51
	v_cvt_pk_bf16_f32 v50, v50, v51
	v_mul_f32_e32 v51, v55, v70
	v_mul_f32_e32 v52, v54, v70
	v_mul_f32_e32 v51, v16, v51
	v_mul_f32_e32 v52, v17, v52
	v_cvt_pk_bf16_f32 v54, v51, v52
	v_mul_f32_e32 v51, v67, v70
	v_mul_f32_e32 v52, v63, v70
	v_mul_f32_e32 v51, v10, v51
	v_mul_f32_e32 v52, v11, v52
	v_cvt_pk_bf16_f32 v51, v51, v52
	v_mul_f32_e32 v52, v57, v70
	v_mul_f32_e32 v53, v56, v70
	v_mul_f32_e32 v52, v18, v52
	v_mul_f32_e32 v53, v19, v53
	v_cvt_pk_bf16_f32 v55, v52, v53
	v_mul_f32_e32 v52, v68, v70
	v_mul_f32_e32 v53, v64, v70
	v_mul_f32_e32 v52, v12, v52
	v_mul_f32_e32 v53, v13, v53
	v_cvt_pk_bf16_f32 v52, v52, v53
	v_mul_f32_e32 v53, v59, v70
	v_mul_f32_e32 v56, v58, v70
	v_mul_f32_e32 v53, v20, v53
	v_mul_f32_e32 v56, v21, v56
	v_cvt_pk_bf16_f32 v56, v53, v56
	v_mul_f32_e32 v53, v69, v70
	v_mul_f32_e32 v57, v65, v70
	v_mul_f32_e32 v53, v14, v53
	v_mul_f32_e32 v57, v15, v57
	v_cvt_pk_bf16_f32 v53, v53, v57
	v_mul_f32_e32 v57, v61, v70
	v_mul_f32_e32 v58, v60, v70
	v_mul_f32_e32 v57, v22, v57
	v_mul_f32_e32 v58, v23, v58
	v_cvt_pk_bf16_f32 v57, v57, v58
	v_lshlrev_b64 v[58:59], 11, v[72:73]
	v_lshl_add_u64 v[58:59], v[4:5], 0, v[58:59]
	global_store_dwordx4 v[58:59], v[50:53], off
	global_store_dwordx4 v[58:59], v[54:57], off offset:16
	global_store_dwordx4 v[32:33], v[24:27], off
	global_store_dwordx4 v[32:33], v[28:31], off offset:16
	v_add_u32_e32 v0, s74, v72
	v_cmp_gt_i32_e32 vcc, s0, v0
	s_nop 4
	s_cbranch_vccnz .Lfin2_check
	s_branch .LBB0_190
	s_nop 0
	s_nop 0
	s_nop 0
	s_nop 0
	s_nop 0
	s_nop 0
	s_nop 0
	s_nop 0
	s_nop 0
	s_nop 0
	s_nop 0
	s_nop 0
	s_nop 0
	s_nop 0
	s_nop 0
	s_nop 0
	s_nop 0
	s_nop 0
	s_nop 0
	s_nop 0
	s_nop 0
	s_nop 0
	s_nop 0
	s_nop 0
	s_nop 0
	s_nop 0
	s_nop 0
	s_nop 0
	s_nop 0
